# comb8 + P0 memory-token norm loop: all 8 gain quads loaded together instead of 7 serialised load/wait(0) round trips (de-serialised prologue work on WGs 0-63)
# baseline (speedup 1.0000x reference)
; __device__ __forceinline__ unsigned cvt_pk_bf16(float lo, float hi) { unsigned r; asm volatile("v_cvt_pk_bf16_f32 %0, %1, %2" : "=v"(r) : "v"(lo), "v"(hi)); return r; }
; #define KIN(i) (*(const float* const __attribute__((address_space(4)))*)(kp + kz + 8 * (i)))
; __global__ void __launch_bounds__(NTHR, 2) fwd_megakernel(Args args) {
;     ...
;             const f32x4* xr = (const f32x4*)(KIN(I_MEM) + (size_t)m * D) + lane; const f32x4* gr = (const f32x4*)KIN(I_MEM_NORM) + lane; u32x2* o = (u32x2*)(MEMN + (size_t)m * D) + lane;
;             f32x4 v[8]; float s = 0.f;
; #pragma unroll
;             for (int j = 0; j < 8; ++j) { v[j] = xr[64 * j]; s += (v[j][0] * v[j][0] + v[j][1] * v[j][1]) + (v[j][2] * v[j][2] + v[j][3] * v[j][3]); }
;             const float rstd = rsqrtf(wave_sum(s) * (1.0f / D) + RMS_EPS);
; #pragma unroll
;             for (int j = 0; j < 8; ++j) { const f32x4 gg = gr[64 * j]; const f32x4 y = v[j] * rstd * gg; u32x2 w; w.x = cvt_pk_bf16(y[0], y[1]); w.y = cvt_pk_bf16(y[2], y[3]); o[64 * j] = w; }
.LBB0_166:
	v_add_co_u32_e32 v0, vcc, 0xfffff000, v16
	global_load_dwordx4 v[26:29], v[16:17], off offset:-3072
	global_load_dwordx4 v[30:33], v[16:17], off offset:-2048
	global_load_dwordx4 v[34:37], v[16:17], off offset:-1024
	v_addc_co_u32_e32 v1, vcc, -1, v17, vcc
	global_load_dwordx4 v[38:41], v[0:1], off offset:-3072
	global_load_dwordx4 v[42:45], v[0:1], off offset:-2048
	global_load_dwordx4 v[46:49], v[0:1], off offset:-1024
	global_load_dwordx4 v[50:53], v[16:17], off offset:-4096
	s_nop 0
	global_load_dwordx4 v[0:3], v[16:17], off
	global_load_dwordx4 v[54:57], v[4:5], off
	global_load_dwordx4 v[130:133], v[4:5], off offset:1024
	global_load_dwordx4 v[134:137], v[4:5], off offset:2048
	global_load_dwordx4 v[138:141], v[4:5], off offset:3072
	global_load_dwordx4 v[142:145], v[6:7], off
	global_load_dwordx4 v[146:149], v[8:9], off
	global_load_dwordx4 v[150:153], v[10:11], off
	global_load_dwordx4 v[154:157], v[12:13], off
	s_add_i32 s66, s66, s68
	s_cmpk_gt_i32 s66, 0x1ff
	v_lshl_add_u64 v[16:17], v[16:17], 0, s[4:5]
	s_waitcnt vmcnt(12)
	v_mov_b32_e32 v68, v39
	v_pk_mul_f32 v[58:59], v[32:33], v[32:33]
	v_pk_mul_f32 v[60:61], v[30:31], v[30:31]
	v_mul_f32_e32 v62, v35, v35
	v_mul_f32_e32 v64, v37, v37
	s_waitcnt vmcnt(8)
	v_mul_f32_e32 v79, v2, v2
	v_mul_f32_e32 v86, v3, v3
	v_pk_mov_b32 v[66:67], v[60:61], v[58:59] op_sel:[1,0]
	v_mov_b32_e32 v61, v59
	v_pk_fma_f32 v[58:59], v[34:35], v[34:35], v[62:63] op_sel_hi:[1,1,0]
	v_pk_fma_f32 v[62:63], v[36:37], v[36:37], v[64:65] op_sel_hi:[1,1,0]
	v_mov_b32_e32 v69, v43
	v_mov_b32_e32 v72, v41
	v_mov_b32_e32 v73, v45
	v_mov_b32_e32 v64, v38
	v_mov_b32_e32 v65, v42
	v_mov_b32_e32 v70, v40
	v_mov_b32_e32 v71, v44
	v_pk_mul_f32 v[74:75], v[48:49], v[48:49]
	v_pk_mul_f32 v[76:77], v[46:47], v[46:47]
	v_pk_add_f32 v[60:61], v[66:67], v[60:61]
	v_mov_b32_e32 v59, v79
	v_mov_b32_e32 v63, v86
	v_pk_mul_f32 v[66:67], v[68:69], v[68:69]
	v_pk_mul_f32 v[68:69], v[72:73], v[72:73]
	v_pk_mov_b32 v[72:73], v[76:77], v[74:75] op_sel:[1,0]
	v_mov_b32_e32 v77, v75
	v_pk_add_f32 v[58:59], v[58:59], v[62:63]
	v_pk_fma_f32 v[62:63], v[64:65], v[64:65], v[66:67]
	v_pk_fma_f32 v[64:65], v[70:71], v[70:71], v[68:69]
	v_mul_f32_e32 v81, v27, v27
	v_mul_f32_e32 v78, v51, v51
	v_mul_f32_e32 v80, v53, v53
	v_pk_add_f32 v[66:67], v[72:73], v[76:77]
	v_pk_add_f32 v[62:63], v[62:63], v[64:65]
	v_mul_f32_e32 v25, v26, v26
	v_mul_f32_e32 v82, v28, v28
	v_mul_f32_e32 v83, v29, v29
	v_pk_fma_f32 v[74:75], v[50:51], v[50:51], v[78:79] op_sel_hi:[1,1,0]
	v_pk_fma_f32 v[78:79], v[52:53], v[52:53], v[80:81] op_sel_hi:[1,1,0]
	v_pk_add_f32 v[64:65], v[66:67], v[66:67] op_sel:[0,1] op_sel_hi:[1,0]
	v_pk_add_f32 v[62:63], v[62:63], v[62:63] op_sel:[0,1] op_sel_hi:[1,0]
	v_mov_b32_e32 v75, v82
	v_mov_b32_e32 v79, v83
	v_mov_b32_e32 v65, v81
	v_mov_b32_e32 v63, v25
	v_pk_add_f32 v[66:67], v[74:75], v[78:79]
	v_pk_add_f32 v[62:63], v[62:63], v[64:65]
	v_mul_f32_e32 v84, v0, v0
	v_pk_add_f32 v[62:63], v[62:63], v[66:67]
	v_mul_f32_e32 v85, v1, v1
	v_pk_add_f32 v[60:61], v[60:61], v[60:61] op_sel:[0,1] op_sel_hi:[1,0]
	v_pk_add_f32 v[62:63], v[62:63], v[62:63] op_sel:[0,1] op_sel_hi:[1,0]
	v_mov_b32_e32 v61, v85
	v_mov_b32_e32 v63, v84
	v_pk_add_f32 v[60:61], v[62:63], v[60:61]
	s_nop 0
	v_pk_add_f32 v[58:59], v[60:61], v[58:59]
	s_nop 0
	v_add_f32_e32 v25, v58, v59
	ds_bpermute_b32 v58, v18, v25
	s_waitcnt lgkmcnt(0)
	v_add_f32_e32 v25, v25, v58
	ds_bpermute_b32 v58, v19, v25
	s_waitcnt lgkmcnt(0)
	v_add_f32_e32 v25, v25, v58
	ds_bpermute_b32 v58, v20, v25
	s_waitcnt lgkmcnt(0)
; __device__ __forceinline__ unsigned cvt_pk_bf16(float lo, float hi) { unsigned r; asm volatile("v_cvt_pk_bf16_f32 %0, %1, %2" : "=v"(r) : "v"(lo), "v"(hi)); return r; }
; __global__ void __launch_bounds__(NTHR, 2) fwd_megakernel(Args args) {
;     ...
;             const float rstd = rsqrtf(wave_sum(s) * (1.0f / D) + RMS_EPS);
; #pragma unroll
;             for (int j = 0; j < 8; ++j) { const f32x4 gg = gr[64 * j]; const f32x4 y = v[j] * rstd * gg; u32x2 w; w.x = cvt_pk_bf16(y[0], y[1]); w.y = cvt_pk_bf16(y[2], y[3]); o[64 * j] = w; }
	v_add_f32_e32 v25, v25, v58
	ds_bpermute_b32 v58, v21, v25
	s_waitcnt lgkmcnt(0)
	v_add_f32_e32 v25, v25, v58
	v_mov_b32_e32 v58, v25
	s_nop 1
	v_permlane16_swap_b32_e32 v25, v58
	s_nop 1
	s_waitcnt lgkmcnt(0)
	v_add_f32_e32 v25, v25, v58
	v_mov_b32_e32 v58, v25
	s_nop 1
	v_permlane32_swap_b32_e32 v25, v58
	s_nop 1
	s_waitcnt lgkmcnt(0)
	v_add_f32_e32 v25, v25, v58
	v_fmamk_f32 v25, v25, 0x3a000000, v24
	v_mul_f32_e32 v58, 0x4b800000, v25
	v_cmp_gt_f32_e32 vcc, s6, v25
	s_nop 1
	v_cndmask_b32_e32 v25, v25, v58, vcc
	v_rsq_f32_e32 v25, v25
	s_nop 0
	v_mul_f32_e32 v58, 0x45800000, v25
	v_cndmask_b32_e32 v58, v25, v58, vcc
	v_pk_mul_f32 v[38:39], v[58:59], v[38:39] op_sel_hi:[0,1]
	v_pk_mul_f32 v[40:41], v[58:59], v[40:41] op_sel_hi:[0,1]
	s_waitcnt vmcnt(0)
	v_pk_mul_f32 v[38:39], v[54:55], v[38:39]
	v_pk_mul_f32 v[40:41], v[56:57], v[40:41]
	v_cvt_pk_bf16_f32 v38, v38, v39
	v_pk_mul_f32 v[42:43], v[58:59], v[42:43] op_sel_hi:[0,1]
	v_cvt_pk_bf16_f32 v39, v40, v41
	global_store_dwordx2 v[14:15], v[38:39], off offset:-3584
	s_nop 0
	v_pk_mul_f32 v[44:45], v[58:59], v[44:45] op_sel_hi:[0,1]
	v_pk_mul_f32 v[26:27], v[58:59], v[26:27] op_sel_hi:[0,1]
	v_pk_mul_f32 v[28:29], v[58:59], v[28:29] op_sel_hi:[0,1]
	v_pk_mul_f32 v[30:31], v[58:59], v[30:31] op_sel_hi:[0,1]
	v_pk_mul_f32 v[32:33], v[58:59], v[32:33] op_sel_hi:[0,1]
	v_pk_mul_f32 v[0:1], v[58:59], v[0:1] op_sel_hi:[0,1]
	v_pk_mul_f32 v[2:3], v[58:59], v[2:3] op_sel_hi:[0,1]
	s_nop 0
	v_pk_mul_f32 v[130:131], v[130:131], v[42:43]
	v_pk_mul_f32 v[132:133], v[132:133], v[44:45]
	v_cvt_pk_bf16_f32 v130, v130, v131
	v_pk_mul_f32 v[42:43], v[58:59], v[46:47] op_sel_hi:[0,1]
	v_cvt_pk_bf16_f32 v131, v132, v133
	global_store_dwordx2 v[14:15], v[130:131], off offset:-3072
	s_nop 0
	v_pk_mul_f32 v[44:45], v[58:59], v[48:49] op_sel_hi:[0,1]
	s_nop 0
	v_pk_mul_f32 v[134:135], v[134:135], v[42:43]
	v_pk_mul_f32 v[136:137], v[136:137], v[44:45]
	v_cvt_pk_bf16_f32 v134, v134, v135
	v_pk_mul_f32 v[42:43], v[58:59], v[50:51] op_sel_hi:[0,1]
	v_cvt_pk_bf16_f32 v135, v136, v137
	global_store_dwordx2 v[14:15], v[134:135], off offset:-2560
	s_nop 0
	v_pk_mul_f32 v[44:45], v[58:59], v[52:53] op_sel_hi:[0,1]
	s_nop 0
	v_pk_mul_f32 v[138:139], v[138:139], v[42:43]
	v_pk_mul_f32 v[140:141], v[140:141], v[44:45]
	v_cvt_pk_bf16_f32 v138, v138, v139
	s_nop 0
	v_cvt_pk_bf16_f32 v139, v140, v141
	global_store_dwordx2 v[14:15], v[138:139], off offset:-2048
	s_nop 0
	s_nop 0
	v_pk_mul_f32 v[26:27], v[142:143], v[26:27]
	v_pk_mul_f32 v[28:29], v[144:145], v[28:29]
	v_cvt_pk_bf16_f32 v26, v26, v27
	s_nop 0
	v_cvt_pk_bf16_f32 v27, v28, v29
	global_store_dwordx2 v[14:15], v[26:27], off offset:-1536
	s_nop 0
	s_nop 0
	v_pk_mul_f32 v[146:147], v[146:147], v[30:31]
	v_pk_mul_f32 v[148:149], v[148:149], v[32:33]
	v_cvt_pk_bf16_f32 v146, v146, v147
	v_pk_mul_f32 v[30:31], v[58:59], v[34:35] op_sel_hi:[0,1]
	v_cvt_pk_bf16_f32 v147, v148, v149
	global_store_dwordx2 v[14:15], v[146:147], off offset:-1024
	s_nop 0
	v_pk_mul_f32 v[32:33], v[58:59], v[36:37] op_sel_hi:[0,1]
	s_nop 0
	v_pk_mul_f32 v[150:151], v[150:151], v[30:31]
	v_pk_mul_f32 v[152:153], v[152:153], v[32:33]
	v_cvt_pk_bf16_f32 v150, v150, v151
	s_nop 0
	v_cvt_pk_bf16_f32 v151, v152, v153
	global_store_dwordx2 v[14:15], v[150:151], off offset:-512
	s_nop 0
	s_nop 0
	v_pk_mul_f32 v[0:1], v[154:155], v[0:1]
	v_pk_mul_f32 v[2:3], v[156:157], v[2:3]
	v_cvt_pk_bf16_f32 v0, v0, v1
	s_nop 0
	v_cvt_pk_bf16_f32 v1, v2, v3
	global_store_dwordx2 v[14:15], v[0:1], off
	v_lshl_add_u64 v[14:15], v[14:15], 0, s[2:3]
	s_cbranch_scc0 .LBB0_166
